# ph3 LoRA GEMM: column tiles pn<4 only run the K-tile pair that holds their non-zero block of the block-diagonal LoRA weight (1 of 3 loop iterations); exact (skipped products are zero)
# speedup vs baseline: 1.0057x; 1.0057x over previous
.LBB0_487:
	s_add_u32 s2, s38, 0x18080
	s_addc_u32 s3, s39, 0
	s_add_u32 s49, s28, 0x100
	v_mov_b32_e32 v0, 0
	s_addc_u32 s52, s29, 0
	s_cmp_lt_i32 s48, 4
	s_cselect_b32 s53, 2, -2
	v_mov_b32_e32 v1, v0
	v_mov_b32_e32 v2, v0
	v_mov_b32_e32 v3, v0
	v_mov_b32_e32 v4, v0
	v_mov_b32_e32 v5, v0
	v_mov_b32_e32 v6, v0
	v_mov_b32_e32 v7, v0
	v_mov_b32_e32 v16, v0
	v_mov_b32_e32 v17, v0
	v_mov_b32_e32 v18, v0
	v_mov_b32_e32 v19, v0
	v_mov_b32_e32 v20, v0
	v_mov_b32_e32 v21, v0
	v_mov_b32_e32 v22, v0
	v_mov_b32_e32 v23, v0
	v_mov_b32_e32 v32, v0
	v_mov_b32_e32 v33, v0
	v_mov_b32_e32 v34, v0
	v_mov_b32_e32 v35, v0
	v_mov_b32_e32 v36, v0
	v_mov_b32_e32 v37, v0
	v_mov_b32_e32 v38, v0
	v_mov_b32_e32 v39, v0
	v_mov_b32_e32 v48, v0
	v_mov_b32_e32 v49, v0
	v_mov_b32_e32 v50, v0
	v_mov_b32_e32 v51, v0
	v_mov_b32_e32 v52, v0
	v_mov_b32_e32 v53, v0
	v_mov_b32_e32 v54, v0
	v_mov_b32_e32 v55, v0
	v_mov_b32_e32 v8, v0
	v_mov_b32_e32 v9, v0
	v_mov_b32_e32 v10, v0
	v_mov_b32_e32 v11, v0
	v_mov_b32_e32 v12, v0
	v_mov_b32_e32 v13, v0
	v_mov_b32_e32 v14, v0
	v_mov_b32_e32 v15, v0
	v_mov_b32_e32 v24, v0
	v_mov_b32_e32 v25, v0
	v_mov_b32_e32 v26, v0
	v_mov_b32_e32 v27, v0
	v_mov_b32_e32 v28, v0
	v_mov_b32_e32 v29, v0
	v_mov_b32_e32 v30, v0
	v_mov_b32_e32 v31, v0
	v_mov_b32_e32 v40, v0
	v_mov_b32_e32 v41, v0
	v_mov_b32_e32 v42, v0
	v_mov_b32_e32 v43, v0
	v_mov_b32_e32 v44, v0
	v_mov_b32_e32 v45, v0
	v_mov_b32_e32 v46, v0
	v_mov_b32_e32 v47, v0
	v_mov_b32_e32 v56, v0
	v_mov_b32_e32 v57, v0
	v_mov_b32_e32 v58, v0
	v_mov_b32_e32 v59, v0
	v_mov_b32_e32 v60, v0
	v_mov_b32_e32 v61, v0
	v_mov_b32_e32 v62, v0
	v_mov_b32_e32 v63, v0
	v_mov_b32_e32 v80, v0
	v_mov_b32_e32 v81, v0
	v_mov_b32_e32 v82, v0
	v_mov_b32_e32 v83, v0
	v_mov_b32_e32 v84, v0
	v_mov_b32_e32 v85, v0
	v_mov_b32_e32 v86, v0
	v_mov_b32_e32 v87, v0
	v_mov_b32_e32 v96, v0
	v_mov_b32_e32 v97, v0
	v_mov_b32_e32 v98, v0
	v_mov_b32_e32 v99, v0
	v_mov_b32_e32 v100, v0
	v_mov_b32_e32 v101, v0
	v_mov_b32_e32 v102, v0
	v_mov_b32_e32 v103, v0
	v_mov_b32_e32 v112, v0
	v_mov_b32_e32 v113, v0
	v_mov_b32_e32 v114, v0
	v_mov_b32_e32 v115, v0
	v_mov_b32_e32 v116, v0
	v_mov_b32_e32 v117, v0
	v_mov_b32_e32 v118, v0
	v_mov_b32_e32 v119, v0
	v_mov_b32_e32 v128, v0
	v_mov_b32_e32 v129, v0
	v_mov_b32_e32 v130, v0
	v_mov_b32_e32 v131, v0
	v_mov_b32_e32 v132, v0
	v_mov_b32_e32 v133, v0
	v_mov_b32_e32 v134, v0
	v_mov_b32_e32 v135, v0
	v_mov_b32_e32 v88, v0
	v_mov_b32_e32 v89, v0
	v_mov_b32_e32 v90, v0
	v_mov_b32_e32 v91, v0
	v_mov_b32_e32 v92, v0
	v_mov_b32_e32 v93, v0
	v_mov_b32_e32 v94, v0
	v_mov_b32_e32 v95, v0
	v_mov_b32_e32 v104, v0
	v_mov_b32_e32 v105, v0
	v_mov_b32_e32 v106, v0
	v_mov_b32_e32 v107, v0
	v_mov_b32_e32 v108, v0
	v_mov_b32_e32 v109, v0
	v_mov_b32_e32 v110, v0
	v_mov_b32_e32 v111, v0
	v_mov_b32_e32 v120, v0
	v_mov_b32_e32 v121, v0
	v_mov_b32_e32 v122, v0
	v_mov_b32_e32 v123, v0
	v_mov_b32_e32 v124, v0
	v_mov_b32_e32 v125, v0
	v_mov_b32_e32 v126, v0
	v_mov_b32_e32 v127, v0
	v_mov_b32_e32 v136, v0
	v_mov_b32_e32 v137, v0
	v_mov_b32_e32 v138, v0
	v_mov_b32_e32 v139, v0
	v_mov_b32_e32 v140, v0
	v_mov_b32_e32 v141, v0
	v_mov_b32_e32 v142, v0
	v_mov_b32_e32 v143, v0
